# attention C tile loop: running per-lane K/V tile addresses advanced by the tile stride (5 adds) instead of ~37 64-bit VALU address ops per tile
# speedup vs baseline: 1.0206x; 1.0056x over previous
; __device__ __forceinline__ void attn_c(LAS unsigned char* lds, const Params& P) {
;     ...
;         const bf16_t* kvh = sample ? KVC + KVC_S_OFF + ((size_t)(b * 16 + h) * KC_ROWS) * 128 : KVC + ((size_t)(b * 16 + h) * SEQ) * 128;
;         KVSrc S{kvh, 128, KRB + krow0 * 32, 32, kvh + 64, 128};
;         bf16x8 qf[6]; load_q<6>(qf, QC + qrow * 1536 + h * 96, hi);
.LBB0_2274:
	v_mad_u64_u32 v[0:1], s[4:5], v150, s73, v[144:145]
	v_mov_b32_e32 v2, v1
	v_mad_u64_u32 v[2:3], s[4:5], v151, s73, v[2:3]
	v_mov_b32_e32 v1, v2
	s_mul_i32 s50, s78, 0x60
	v_lshl_add_u64 v[0:1], s[50:51], 1, v[0:1]
	v_lshl_add_u64 v[0:1], v[0:1], 0, v[146:147]
	global_load_dwordx4 v[96:99], v[0:1], off
	global_load_dwordx4 v[100:103], v[0:1], off offset:32
	global_load_dwordx4 v[104:107], v[0:1], off offset:64
	global_load_dwordx4 v[108:111], v[0:1], off offset:96
	global_load_dwordx4 v[112:115], v[0:1], off offset:128
	global_load_dwordx4 v[116:119], v[0:1], off offset:160
	v_mov_b32_e32 v17, v254
	s_lshl_b64 s[2:3], s[2:3], 6
	v_mul_hi_i32 v0, v17, s74
	v_lshrrev_b32_e32 v1, 31, v0
	v_ashrrev_i32_e32 v0, 1, v0
	v_add_u32_e32 v152, v0, v1
	v_mul_lo_u32 v0, v152, 12
	v_sub_u32_e32 v18, v17, v0
	s_add_u32 s8, s33, s2
	v_lshlrev_b32_e32 v8, 3, v18
	s_addc_u32 s9, s70, s3
	v_ashrrev_i32_e32 v153, 31, v152
	v_cmp_lt_i32_e64 s[2:3], 7, v18
	v_cmp_gt_i32_e32 vcc, 8, v18
	v_ashrrev_i32_e32 v9, 31, v8
	s_and_saveexec_b64 s[4:5], vcc
	s_xor_b64 s[4:5], exec, s[4:5]
	v_lshlrev_b64 v[0:1], 8, v[152:153]
	v_lshl_add_u64 v[0:1], s[0:1], 0, v[0:1]
	v_lshl_add_u64 v[0:1], v[8:9], 1, v[0:1]
	s_andn2_saveexec_b64 s[4:5], s[4:5]
	v_lshlrev_b64 v[0:1], 6, v[152:153]
	v_lshl_add_u64 v[0:1], s[8:9], 0, v[0:1]
	v_mov_b32_e32 v142, v8
	v_lshl_add_u64 v[0:1], v[142:143], 1, v[0:1]
	v_lshl_add_u64 v[0:1], v[0:1], 0, s[58:59]
	s_or_b64 exec, exec, s[4:5]
	global_load_dwordx4 v[0:3], v[0:1], off
	s_waitcnt vmcnt(0)
	v_add_u32_e32 v20, 0x200, v17
	v_mul_hi_i32 v4, v20, s74
	v_lshrrev_b32_e32 v5, 31, v4
	v_ashrrev_i32_e32 v4, 1, v4
	v_add_u32_e32 v154, v4, v5
	v_mul_lo_u32 v4, v154, 12
	v_sub_u32_e32 v19, v20, v4
	v_lshlrev_b32_e32 v10, 3, v19
	v_ashrrev_i32_e32 v155, 31, v154
	v_cmp_lt_i32_e64 s[4:5], 7, v19
	v_cmp_gt_i32_e32 vcc, 8, v19
	v_ashrrev_i32_e32 v11, 31, v10
	s_and_saveexec_b64 s[6:7], vcc
	s_xor_b64 s[6:7], exec, s[6:7]
	v_lshlrev_b64 v[4:5], 8, v[154:155]
	v_lshl_add_u64 v[4:5], s[0:1], 0, v[4:5]
	v_lshl_add_u64 v[4:5], v[10:11], 1, v[4:5]
	s_andn2_saveexec_b64 s[6:7], s[6:7]
	v_lshlrev_b64 v[4:5], 6, v[154:155]
	v_lshl_add_u64 v[4:5], s[8:9], 0, v[4:5]
	v_mov_b32_e32 v142, v10
	v_lshl_add_u64 v[4:5], v[142:143], 1, v[4:5]
	v_lshl_add_u64 v[4:5], v[4:5], 0, s[58:59]
	s_or_b64 exec, exec, s[6:7]
	global_load_dwordx4 v[4:7], v[4:5], off
	v_add_u32_e32 v12, 0x400, v17
	v_mul_hi_i32 v13, v12, s74
	v_lshrrev_b32_e32 v14, 31, v13
	v_ashrrev_i32_e32 v13, 1, v13
	v_add_u32_e32 v156, v13, v14
	v_mul_lo_u32 v13, v156, 12
	v_sub_u32_e32 v21, v12, v13
	v_lshlrev_b32_e32 v142, 3, v21
	v_ashrrev_i32_e32 v157, 31, v156
	v_cmp_lt_i32_e64 s[6:7], 7, v21
	v_cmp_gt_i32_e32 vcc, 8, v21
	v_mov_b64_e32 v[12:13], v[142:143]
	s_and_saveexec_b64 s[10:11], vcc
	s_xor_b64 s[10:11], exec, s[10:11]
	v_lshlrev_b64 v[12:13], 8, v[156:157]
	v_lshl_add_u64 v[14:15], s[0:1], 0, v[12:13]
	v_ashrrev_i32_e32 v13, 31, v142
	v_mov_b32_e32 v12, v142
	v_lshl_add_u64 v[14:15], v[12:13], 1, v[14:15]
	s_andn2_saveexec_b64 s[10:11], s[10:11]
	v_lshlrev_b64 v[14:15], 6, v[156:157]
	v_lshl_add_u64 v[14:15], s[8:9], 0, v[14:15]
	v_lshl_add_u64 v[14:15], v[142:143], 1, v[14:15]
	v_lshl_add_u64 v[14:15], v[14:15], 0, s[58:59]
	s_or_b64 exec, exec, s[10:11]
	global_load_dwordx4 v[22:25], v[14:15], off
	v_ashrrev_i32_e32 v14, 31, v17
	v_lshrrev_b32_e32 v14, 29, v14
	v_add_u32_e32 v14, v17, v14
	v_ashrrev_i32_e32 v158, 3, v14
	v_and_b32_e32 v14, -8, v14
	v_sub_u32_e32 v38, v17, v14
	v_lshlrev_b32_e32 v26, 3, v38
	v_ashrrev_i32_e32 v27, 31, v26
	v_lshlrev_b64 v[34:35], 1, v[26:27]
	v_ashrrev_i32_e32 v26, 31, v20
	v_lshrrev_b32_e32 v26, 29, v26
	v_add_u32_e32 v26, v20, v26
	v_ashrrev_i32_e32 v160, 3, v26
	v_and_b32_e32 v26, -8, v26
	v_sub_u32_e32 v20, v20, v26
	v_ashrrev_i32_e32 v159, 31, v158
	v_ashrrev_i32_e32 v161, 31, v160
	v_lshlrev_b32_e32 v28, 3, v20
	v_lshlrev_b64 v[14:15], 8, v[158:159]
	v_lshlrev_b64 v[26:27], 8, v[160:161]
	v_ashrrev_i32_e32 v29, 31, v28
	v_lshl_add_u64 v[14:15], s[0:1], 0, v[14:15]
	v_lshl_add_u64 v[26:27], s[0:1], 0, v[26:27]
	v_lshlrev_b64 v[36:37], 1, v[28:29]
	v_lshl_add_u64 v[14:15], v[14:15], 0, v[34:35]
	v_lshl_add_u64 v[30:31], v[26:27], 0, v[36:37]
	global_load_dwordx4 v[26:29], v[14:15], off offset:128
	s_waitcnt lgkmcnt(0)
; template <int DQK, int DV, bool BIAS, int TK> ...
;     ...
;     ATT_LOAD(t0); ATT_STORE(0); __syncthreads();
; __device__ __forceinline__ void attn_c(LAS unsigned char* lds, const Params& P) {
;     ...
;         f32x16 o[2];
; #pragma unroll
;         for (int db = 0; db < 2; ++db)
; #pragma unroll
;             for (int r = 0; r < 16; ++r) o[db][r] = 0.f;
;         float m_run = NEGBIG, l_run = 0.f;
	global_load_dwordx4 v[30:33], v[30:31], off offset:128
	v_bfe_u32 v40, v17, 5, 1
	v_mul_lo_u32 v149, v152, s75
	v_lshlrev_b32_e32 v184, 4, v18
	v_mul_lo_u32 v185, v154, s75
	v_lshlrev_b32_e32 v186, 4, v19
	v_lshlrev_b32_e32 v188, 4, v21
	v_lshrrev_b32_e32 v19, 2, v17
	v_and_b32_e32 v21, 16, v17
	v_lshlrev_b32_e32 v41, 2, v17
	v_mov_b32_e32 v14, v8
	v_lshl_add_u64 v[162:163], v[8:9], 1, s[0:1]
	v_add3_u32 v8, 0, v149, v184
	v_lshlrev_b32_e32 v191, 2, v40
	v_lshlrev_b32_e32 v39, 6, v16
	v_lshl_add_u64 v[166:167], v[12:13], 1, s[0:1]
	v_add3_u32 v9, 0, v185, v186
	v_and_or_b32 v13, v41, 12, v21
	ds_write_b128 v8, v[0:3] offset:1024
	s_waitcnt vmcnt(3)
	ds_write_b128 v9, v[4:7] offset:1024
	v_and_or_b32 v0, v19, 3, v191
	v_mul_lo_u32 v187, v156, s75
	v_and_b32_e32 v18, 31, v17
	v_mov_b32_e32 v15, v143
	v_min_i32_e32 v190, s12, v39
	v_lshlrev_b32_e32 v1, 1, v13
	v_mul_u32_u24_e32 v0, 0xc0, v0
	v_mul_lo_u32 v194, v158, s76
	v_mul_lo_u32 v195, v160, s76
	v_lshlrev_b32_e32 v197, 4, v38
	v_lshlrev_b32_e32 v198, 4, v20
	v_mov_b32_e32 v201, 0
	v_cmp_lt_i32_e32 vcc, 0, v16
	v_mov_b32_e32 v16, v10
	v_mov_b32_e32 v17, v143
	v_lshl_add_u64 v[164:165], v[10:11], 1, s[0:1]
	v_add3_u32 v10, 0, v187, v188
	v_mul_u32_u24_e32 v11, 0xd0, v18
	v_lshlrev_b32_e32 v12, 4, v40
	v_lshl_add_u64 v[170:171], v[14:15], 1, s[8:9]
	v_add_u32_e32 v14, 0x7f, v190
	v_add3_u32 v196, 0, v0, v1
	v_add3_u32 v0, 0, v194, v197
	v_add3_u32 v1, 0, v195, v198
	s_add_i32 s50, s79, -1
	v_lshl_add_u64 v[168:169], v[142:143], 1, s[8:9]
	s_lshl_b32 s80, s79, 7
	s_mov_b64 s[62:63], 0
	s_mov_b32 s10, 0
	v_mov_b32_e32 v189, 0
	v_lshl_add_u64 v[172:173], v[16:17], 1, s[8:9]
	s_xor_b64 s[64:65], vcc, -1
	v_add3_u32 v192, 0, v11, v12
	v_lshrrev_b32_e32 v193, 7, v14
	v_lshl_add_u64 v[174:175], s[0:1], 0, v[34:35]
	v_lshl_add_u64 v[176:177], s[0:1], 0, v[36:37]
	v_mov_b32_e32 v200, 0
	v_mov_b32_e32 v16, 0
	v_mov_b32_e32 v17, v201
	v_mov_b32_e32 v18, v201
	v_mov_b32_e32 v19, v201
	v_mov_b32_e32 v20, v201
	v_mov_b32_e32 v21, v201
	v_mov_b32_e32 v2, v201
	v_mov_b32_e32 v3, v201
	v_mov_b32_e32 v4, v201
	v_mov_b32_e32 v5, v201
	v_mov_b32_e32 v6, v201
	v_mov_b32_e32 v7, v201
	v_mov_b32_e32 v8, v201
	s_waitcnt vmcnt(2)
	ds_write_b128 v10, v[22:25] offset:1024
	s_waitcnt vmcnt(1)
	ds_write_b128 v0, v[26:29] offset:54272
	s_waitcnt vmcnt(0)
	ds_write_b128 v1, v[30:33] offset:54272
	v_mov_b32_e32 v22, v201
	v_mov_b32_e32 v23, v201
	v_mov_b32_e32 v24, v201
	v_mov_b32_e32 v25, v201
	v_mov_b32_e32 v26, v201
	v_mov_b32_e32 v27, v201
	v_mov_b32_e32 v28, v201
	v_mov_b32_e32 v29, v201
	v_mov_b32_e32 v30, v201
	v_mov_b32_e32 v31, v201
	v_mov_b32_e32 v0, v201
	v_mov_b32_e32 v1, v201
	v_mov_b32_e32 v9, v201
	v_mov_b32_e32 v10, v201
	v_mov_b32_e32 v11, v201
	v_mov_b32_e32 v12, v201
	v_mov_b32_e32 v13, v201
	v_mov_b32_e32 v14, v201
	v_mov_b32_e32 v15, v201
	s_waitcnt lgkmcnt(0)
	s_barrier
	s_mov_b32 s0, s10
	s_ashr_i32 s1, s0, 31
	s_lshl_b64 s[0:1], s[0:1], 7
	v_lshl_add_u64 v[32:33], s[0:1], 0, v[152:153]
	v_lshlrev_b64 v[34:35], 6, v[32:33]
	v_lshl_add_u64 v[34:35], v[170:171], 0, v[34:35]
	v_lshlrev_b64 v[32:33], 8, v[32:33]
	v_lshl_add_u64 v[34:35], v[34:35], 0, s[58:59]
	v_lshl_add_u64 v[32:33], v[162:163], 0, v[32:33]
	v_cndmask_b32_e64 v33, v33, v35, s[2:3]
	v_cndmask_b32_e64 v32, v32, v34, s[2:3]
	v_mov_b32_e32 v226, v32
	v_mov_b32_e32 v227, v33
	v_lshl_add_u64 v[32:33], s[0:1], 0, v[154:155]
	v_lshlrev_b64 v[34:35], 6, v[32:33]
	v_lshl_add_u64 v[34:35], v[172:173], 0, v[34:35]
	v_lshlrev_b64 v[32:33], 8, v[32:33]
	v_lshl_add_u64 v[34:35], v[34:35], 0, s[58:59]
	v_lshl_add_u64 v[32:33], v[164:165], 0, v[32:33]
	v_cndmask_b32_e64 v33, v33, v35, s[4:5]
	v_cndmask_b32_e64 v32, v32, v34, s[4:5]
	v_mov_b32_e32 v228, v32
	v_mov_b32_e32 v229, v33
	v_lshl_add_u64 v[32:33], s[0:1], 0, v[156:157]
	v_lshlrev_b64 v[34:35], 6, v[32:33]
	v_lshl_add_u64 v[34:35], v[168:169], 0, v[34:35]
	v_lshlrev_b64 v[32:33], 8, v[32:33]
	v_lshl_add_u64 v[34:35], v[34:35], 0, s[58:59]
	v_lshl_add_u64 v[32:33], v[166:167], 0, v[32:33]
	v_cndmask_b32_e64 v33, v33, v35, s[6:7]
	v_cndmask_b32_e64 v32, v32, v34, s[6:7]
	v_mov_b32_e32 v230, v32
	v_mov_b32_e32 v231, v33
	v_lshl_add_u64 v[32:33], s[0:1], 0, v[158:159]
	v_lshlrev_b64 v[32:33], 8, v[32:33]
	v_lshl_add_u64 v[34:35], s[0:1], 0, v[160:161]
	v_lshl_add_u64 v[32:33], v[174:175], 0, v[32:33]
	v_lshlrev_b64 v[34:35], 8, v[34:35]
	v_lshl_add_u64 v[34:35], v[176:177], 0, v[34:35]
	v_mov_b32_e32 v232, v32
	v_mov_b32_e32 v233, v33
	v_mov_b32_e32 v234, v34
	v_mov_b32_e32 v235, v35
	v_mov_b32_e32 v242, 0x8000
	v_mov_b32_e32 v243, 0x2000
	v_cndmask_b32_e64 v236, v242, v243, s[2:3]
	v_mov_b32_e32 v237, 0
	v_cndmask_b32_e64 v238, v242, v243, s[4:5]
	v_mov_b32_e32 v239, 0
	v_cndmask_b32_e64 v240, v242, v243, s[6:7]
	v_mov_b32_e32 v241, 0
	s_branch .LBB0_2291

; #define LAS __attribute__((address_space(3)))
; template <int DQK, int DV, bool BIAS, int TK> ...
;     ...
;     for (int t = t0; t < t1; ++t) {
;         const int cur = (t - t0) & 1;
;         ATT_LOAD((t + 1 < t1 ? t + 1 : t1 - 1));
;         if (t >= w0 && t < w1) {
;             const LAS unsigned char* kb = kb0 + cur * KBUF + koff; const LAS unsigned char* vb = vb0 + cur * VBUF + voff;
;             f32x16 p[NPB];
;             const int tk0 = t * TK;
;             const bool far = BIAS && (qpos_w0 - (kpos0 + tk0 + TK - 64) >= 192);
;             const float pinit = far ? tab[254] : 0.f;
; #pragma unroll
;             for (int q = 0; q < NPB; ++q)
; #pragma unroll
;                 for (int r = 0; r < 16; ++r) p[q][r] = pinit - m_run;
; #pragma unroll
;             for (int ks = 0; ks < DQK / 16; ++ks)
; #pragma unroll
;                 for (int q = 0; q < NPB; ++q) {
;                     const bf16x8 a = *(const LAS bf16x8*)(kb + q * 32 * KP + ks * 32);
;                     p[q] = __builtin_amdgcn_mfma_f32_32x32x16_bf16(a, qf[ks], p[q], 0, 0, 0);
;                 }
;             __builtin_amdgcn_sched_barrier(0);
;             asm volatile("s_nop 15\n\ts_nop 15" ::: "memory");
.LBB0_2291:
	s_add_i32 s81, s10, 1
	s_cmp_lt_u32 s81, s79
	s_cbranch_scc0 .Lattadv_skip2291
	s_mov_b64 s[0:1], 0x8000
	v_lshl_add_u64 v[226:227], v[226:227], 0, v[236:237]
	v_lshl_add_u64 v[228:229], v[228:229], 0, v[238:239]
	v_lshl_add_u64 v[230:231], v[230:231], 0, v[240:241]
	v_lshl_add_u64 v[232:233], v[232:233], 0, s[0:1]
	v_lshl_add_u64 v[234:235], v[234:235], 0, s[0:1]
.Lattadv_skip2291:
	global_load_dwordx4 v[120:123], v[226:227], off
	global_load_dwordx4 v[124:127], v[228:229], off
	global_load_dwordx4 v[128:131], v[230:231], off
	global_load_dwordx4 v[136:139], v[232:233], off offset:128
	global_load_dwordx4 v[132:135], v[234:235], off offset:128
	v_cmp_ge_u32_e32 vcc, s10, v193
	s_or_b64 s[0:1], s[64:65], vcc
	v_add_u32_e32 v199, 0x80, v201
	s_and_saveexec_b64 s[8:9], s[0:1]
	s_xor_b64 s[0:1], exec, s[8:9]
	v_add_u32_e32 v199, 0x80, v201
	s_or_saveexec_b64 s[66:67], s[0:1]
	s_and_b32 s82, s10, 1
	s_xor_b64 exec, exec, s[66:67]
	s_cbranch_execz .LBB0_2290
	s_mul_i32 s0, s82, 0x6800
	v_add_u32_e32 v142, s0, v192
	ds_read_b128 v[48:51], v142 offset:1024
	ds_read_b128 v[202:205], v142 offset:1056
	v_sub_f32_e32 v32, 0, v189
	v_mov_b32_e32 v33, v32
	v_mov_b32_e32 v34, v32
	v_mov_b32_e32 v35, v32
	v_mov_b32_e32 v36, v32
	v_mov_b32_e32 v37, v32
	v_mov_b32_e32 v38, v32
	v_mov_b32_e32 v39, v32
	v_mov_b32_e32 v40, v32
	v_mov_b32_e32 v41, v32
	v_mov_b32_e32 v42, v32
	v_mov_b32_e32 v43, v32
	v_mov_b32_e32 v44, v32
	v_mov_b32_e32 v45, v32
	v_mov_b32_e32 v46, v32
	v_mov_b32_e32 v47, v32
	s_waitcnt lgkmcnt(1)
	s_nop 0
	v_mfma_f32_32x32x16_bf16 v[80:95], v[48:51], v[96:99], v[32:47]
	ds_read_b128 v[48:51], v142 offset:7680
	ds_read_b128 v[206:209], v142 offset:7712
	ds_read_b128 v[210:213], v142 offset:14336
	ds_read_b128 v[214:217], v142 offset:14368
	s_waitcnt lgkmcnt(3)
	v_mfma_f32_32x32x16_bf16 v[64:79], v[48:51], v[96:99], v[32:47]
	s_waitcnt lgkmcnt(1)
	v_mfma_f32_32x32x16_bf16 v[48:63], v[210:213], v[96:99], v[32:47]
	ds_read_b128 v[210:213], v142 offset:20992
	ds_read_b128 v[218:221], v142 offset:21024
	v_mfma_f32_32x32x16_bf16 v[80:95], v[202:205], v[100:103], v[80:95]
	s_waitcnt lgkmcnt(1)
	v_mfma_f32_32x32x16_bf16 v[32:47], v[210:213], v[96:99], v[32:47]
	v_mfma_f32_32x32x16_bf16 v[64:79], v[206:209], v[100:103], v[64:79]
	ds_read_b128 v[202:205], v142 offset:1088
	ds_read_b128 v[206:209], v142 offset:1120
	v_mfma_f32_32x32x16_bf16 v[48:63], v[214:217], v[100:103], v[48:63]
	s_waitcnt lgkmcnt(1)
	v_mfma_f32_32x32x16_bf16 v[80:95], v[202:205], v[104:107], v[80:95]
	ds_read_b128 v[202:205], v142 offset:7744
	ds_read_b128 v[210:213], v142 offset:7776
	v_mfma_f32_32x32x16_bf16 v[32:47], v[218:221], v[100:103], v[32:47]
	s_waitcnt lgkmcnt(1)
	v_mfma_f32_32x32x16_bf16 v[64:79], v[202:205], v[104:107], v[64:79]
	ds_read_b128 v[202:205], v142 offset:14400
	ds_read_b128 v[214:217], v142 offset:14432
	s_waitcnt lgkmcnt(1)
	v_mfma_f32_32x32x16_bf16 v[48:63], v[202:205], v[104:107], v[48:63]
	ds_read_b128 v[202:205], v142 offset:21056
	ds_read_b128 v[218:221], v142 offset:21088
	v_mfma_f32_32x32x16_bf16 v[80:95], v[206:209], v[108:111], v[80:95]
	s_waitcnt lgkmcnt(1)
	v_mfma_f32_32x32x16_bf16 v[32:47], v[202:205], v[104:107], v[32:47]
	ds_read_b128 v[202:205], v142 offset:1152
	ds_read_b128 v[206:209], v142 offset:1184
	v_mfma_f32_32x32x16_bf16 v[64:79], v[210:213], v[108:111], v[64:79]
	v_mfma_f32_32x32x16_bf16 v[48:63], v[214:217], v[108:111], v[48:63]
	s_waitcnt lgkmcnt(1)
	v_mfma_f32_32x32x16_bf16 v[80:95], v[202:205], v[112:115], v[80:95]
	ds_read_b128 v[202:205], v142 offset:7808
	ds_read_b128 v[210:213], v142 offset:7840
	v_mfma_f32_32x32x16_bf16 v[32:47], v[218:221], v[108:111], v[32:47]
	s_waitcnt lgkmcnt(1)
	v_mfma_f32_32x32x16_bf16 v[64:79], v[202:205], v[112:115], v[64:79]
	ds_read_b128 v[202:205], v142 offset:14464
	ds_read_b128 v[214:217], v142 offset:14496
	s_waitcnt lgkmcnt(1)
	v_mfma_f32_32x32x16_bf16 v[48:63], v[202:205], v[112:115], v[48:63]
	ds_read_b128 v[202:205], v142 offset:21120
	ds_read_b128 v[218:221], v142 offset:21152
	s_waitcnt lgkmcnt(1)
	v_mfma_f32_32x32x16_bf16 v[32:47], v[202:205], v[112:115], v[32:47]
	v_mfma_f32_32x32x16_bf16 v[80:95], v[206:209], v[116:119], v[80:95]
	v_mfma_f32_32x32x16_bf16 v[64:79], v[210:213], v[116:119], v[64:79]
	v_mfma_f32_32x32x16_bf16 v[48:63], v[214:217], v[116:119], v[48:63]
	s_waitcnt lgkmcnt(0)
	v_mfma_f32_32x32x16_bf16 v[32:47], v[218:221], v[116:119], v[32:47]
	s_nop 15
	s_nop 15
	v_cmp_gt_i32_e32 vcc, v199, v190
	s_and_saveexec_b64 s[68:69], vcc
	s_cbranch_execz .LBB0_2287
; template <int DQK, int DV, bool BIAS, int TK> ...
;     ...
;             if (tk0 < klo || tk0 + TK > khi) {
;                 asm volatile("" ::: "memory");
; #pragma unroll
;                 for (int q = 0; q < NPB; ++q)
; #pragma unroll
;                     for (int r = 0; r < 16; ++r) { const int key = tk0 + 32 * q + 4 * hi + (r & 3) + 8 * (r >> 2); if (key < klo || key >= khi) p[q][r] = NEGBIG; }
;             }
	v_add_u32_e32 v142, v191, v201
	v_add_u32_e32 v178, 1, v142
	v_cmp_lt_i32_e64 s[0:1], v178, v190
	v_add_u32_e32 v178, 2, v142
	v_cmp_lt_i32_e64 s[8:9], v178, v190
	v_add_u32_e32 v178, 3, v142
	v_cmp_lt_i32_e64 s[10:11], v178, v190
	v_add_u32_e32 v178, 8, v142
	v_cmp_lt_i32_e64 s[12:13], v178, v190
	v_add_u32_e32 v178, 9, v142
	v_cmp_lt_i32_e64 s[14:15], v178, v190
	v_add_u32_e32 v178, 10, v142
	v_cmp_lt_i32_e64 s[20:21], v178, v190
	v_add_u32_e32 v178, 11, v142
	v_cmp_lt_i32_e64 s[22:23], v178, v190
	v_add_u32_e32 v178, 16, v142
	v_cmp_lt_i32_e64 s[24:25], v178, v190
	v_add_u32_e32 v178, 17, v142
	v_cmp_lt_i32_e64 s[26:27], v178, v190
	v_add_u32_e32 v178, 18, v142
	v_cmp_lt_i32_e64 s[28:29], v178, v190
	v_add_u32_e32 v178, 19, v142
	v_cmp_lt_i32_e64 s[30:31], v178, v190
	v_add_u32_e32 v178, 24, v142
	v_cmp_lt_i32_e64 s[34:35], v178, v190
	v_add_u32_e32 v178, 25, v142
	v_cmp_lt_i32_e64 s[36:37], v178, v190
	v_add_u32_e32 v178, 26, v142
	v_cmp_lt_i32_e64 s[38:39], v178, v190
	v_add_u32_e32 v178, 27, v142
	v_cmp_lt_i32_e64 s[40:41], v178, v190
	s_or_b64 s[38:39], s[40:41], s[38:39]
	s_or_b64 s[36:37], s[38:39], s[36:37]
	s_or_b64 s[34:35], s[36:37], s[34:35]
	s_or_b64 s[30:31], s[34:35], s[30:31]
	s_or_b64 s[28:29], s[30:31], s[28:29]
	s_or_b64 s[26:27], s[28:29], s[26:27]
	s_or_b64 s[24:25], s[26:27], s[24:25]
	s_or_b64 s[22:23], s[24:25], s[22:23]
	s_or_b64 s[20:21], s[22:23], s[20:21]
	s_or_b64 s[14:15], s[20:21], s[14:15]
	s_or_b64 s[12:13], s[14:15], s[12:13]
	s_or_b64 s[10:11], s[12:13], s[10:11]
	s_or_b64 s[8:9], s[10:11], s[8:9]
	v_cmp_lt_i32_e32 vcc, v142, v190
	s_or_b64 s[0:1], s[8:9], s[0:1]
	s_or_b64 vcc, s[0:1], vcc
	v_add_u32_e32 v178, 32, v142
	v_cndmask_b32_e32 v80, v182, v80, vcc
	v_cmp_lt_i32_e32 vcc, v178, v190
	v_add_u32_e32 v178, 33, v142
	v_cndmask_b32_e64 v81, v182, v81, s[0:1]
	v_cmp_lt_i32_e64 s[0:1], v178, v190
	v_add_u32_e32 v178, 34, v142
	v_cndmask_b32_e64 v82, v182, v82, s[8:9]
	v_cmp_lt_i32_e64 s[8:9], v178, v190
	v_add_u32_e32 v178, 35, v142
	v_cndmask_b32_e64 v83, v182, v83, s[10:11]
	v_cmp_lt_i32_e64 s[10:11], v178, v190
	v_add_u32_e32 v178, 40, v142
	v_cndmask_b32_e64 v84, v182, v84, s[12:13]
	v_cmp_lt_i32_e64 s[12:13], v178, v190
	v_add_u32_e32 v178, 41, v142
	v_cndmask_b32_e64 v85, v182, v85, s[14:15]
	v_cmp_lt_i32_e64 s[14:15], v178, v190
	v_add_u32_e32 v178, 42, v142
	v_cndmask_b32_e64 v86, v182, v86, s[20:21]
	v_cmp_lt_i32_e64 s[20:21], v178, v190
	v_add_u32_e32 v178, 43, v142
	v_cndmask_b32_e64 v87, v182, v87, s[22:23]
	v_cmp_lt_i32_e64 s[22:23], v178, v190
	v_add_u32_e32 v178, 48, v142
	v_cndmask_b32_e64 v88, v182, v88, s[24:25]
	v_cmp_lt_i32_e64 s[24:25], v178, v190
	v_add_u32_e32 v178, 49, v142
	v_cndmask_b32_e64 v89, v182, v89, s[26:27]
	v_cmp_lt_i32_e64 s[26:27], v178, v190
	v_add_u32_e32 v178, 50, v142
	v_cndmask_b32_e64 v90, v182, v90, s[28:29]
	v_cmp_lt_i32_e64 s[28:29], v178, v190
	v_add_u32_e32 v178, 51, v142
	v_cndmask_b32_e64 v91, v182, v91, s[30:31]
	v_cmp_lt_i32_e64 s[30:31], v178, v190
	v_add_u32_e32 v178, 56, v142
	v_cndmask_b32_e64 v92, v182, v92, s[34:35]
	v_cmp_lt_i32_e64 s[34:35], v178, v190
	v_add_u32_e32 v178, 57, v142
	v_cndmask_b32_e64 v93, v182, v93, s[36:37]
	v_cmp_lt_i32_e64 s[36:37], v178, v190
	v_add_u32_e32 v178, 58, v142
	v_cndmask_b32_e64 v94, v182, v94, s[38:39]
	v_cmp_lt_i32_e64 s[38:39], v178, v190
	v_add_u32_e32 v178, 59, v142
	v_cndmask_b32_e64 v95, v182, v95, s[40:41]
	v_cmp_lt_i32_e64 s[40:41], v178, v190
	s_or_b64 s[38:39], s[40:41], s[38:39]
	s_or_b64 s[36:37], s[38:39], s[36:37]
	s_or_b64 s[34:35], s[36:37], s[34:35]
	s_or_b64 s[30:31], s[34:35], s[30:31]
	s_or_b64 s[28:29], s[30:31], s[28:29]
	s_or_b64 s[26:27], s[28:29], s[26:27]
	s_or_b64 s[24:25], s[26:27], s[24:25]
	s_or_b64 s[22:23], s[24:25], s[22:23]
	s_or_b64 s[20:21], s[22:23], s[20:21]
	s_or_b64 s[14:15], s[20:21], s[14:15]
	s_or_b64 s[12:13], s[14:15], s[12:13]
	s_or_b64 s[10:11], s[12:13], s[10:11]
	s_or_b64 s[8:9], s[10:11], s[8:9]
	s_or_b64 s[0:1], s[8:9], s[0:1]
	s_or_b64 vcc, s[0:1], vcc
	v_add_u32_e32 v178, 64, v142
	v_cndmask_b32_e32 v64, v182, v64, vcc
	v_cmp_lt_i32_e32 vcc, v178, v190
	v_add_u32_e32 v178, 0x41, v142
	v_cndmask_b32_e64 v65, v182, v65, s[0:1]
	v_cmp_lt_i32_e64 s[0:1], v178, v190
	v_add_u32_e32 v178, 0x42, v142
	v_cndmask_b32_e64 v66, v182, v66, s[8:9]
	v_cmp_lt_i32_e64 s[8:9], v178, v190
	v_add_u32_e32 v178, 0x43, v142
	v_cndmask_b32_e64 v67, v182, v67, s[10:11]
	v_cmp_lt_i32_e64 s[10:11], v178, v190
	v_add_u32_e32 v178, 0x48, v142
	v_cndmask_b32_e64 v68, v182, v68, s[12:13]
	v_cmp_lt_i32_e64 s[12:13], v178, v190
	v_add_u32_e32 v178, 0x49, v142
	v_cndmask_b32_e64 v69, v182, v69, s[14:15]
	v_cmp_lt_i32_e64 s[14:15], v178, v190
	v_add_u32_e32 v178, 0x4a, v142
	v_cndmask_b32_e64 v70, v182, v70, s[20:21]
; template <int DQK, int DV, bool BIAS, int TK> ...
;     ...
;             if (tk0 < klo || tk0 + TK > khi) {
;                 asm volatile("" ::: "memory");
; #pragma unroll
;                 for (int q = 0; q < NPB; ++q)
; #pragma unroll
;                     for (int r = 0; r < 16; ++r) { const int key = tk0 + 32 * q + 4 * hi + (r & 3) + 8 * (r >> 2); if (key < klo || key >= khi) p[q][r] = NEGBIG; }
;             }
	v_cmp_lt_i32_e64 s[20:21], v178, v190
	v_add_u32_e32 v178, 0x4b, v142
	v_cndmask_b32_e64 v71, v182, v71, s[22:23]
	v_cmp_lt_i32_e64 s[22:23], v178, v190
	v_add_u32_e32 v178, 0x50, v142
	v_cndmask_b32_e64 v72, v182, v72, s[24:25]
	v_cmp_lt_i32_e64 s[24:25], v178, v190
	v_add_u32_e32 v178, 0x51, v142
	v_cndmask_b32_e64 v73, v182, v73, s[26:27]
	v_cmp_lt_i32_e64 s[26:27], v178, v190
	v_add_u32_e32 v178, 0x52, v142
	v_cndmask_b32_e64 v74, v182, v74, s[28:29]
	v_cmp_lt_i32_e64 s[28:29], v178, v190
	v_add_u32_e32 v178, 0x53, v142
	v_cndmask_b32_e64 v75, v182, v75, s[30:31]
	v_cmp_lt_i32_e64 s[30:31], v178, v190
	v_add_u32_e32 v178, 0x58, v142
	v_cndmask_b32_e64 v76, v182, v76, s[34:35]
	v_cmp_lt_i32_e64 s[34:35], v178, v190
	v_add_u32_e32 v178, 0x59, v142
	v_cndmask_b32_e64 v77, v182, v77, s[36:37]
	v_cmp_lt_i32_e64 s[36:37], v178, v190
	v_add_u32_e32 v178, 0x5a, v142
	v_cndmask_b32_e64 v78, v182, v78, s[38:39]
	v_cmp_lt_i32_e64 s[38:39], v178, v190
	v_add_u32_e32 v178, 0x5b, v142
	v_cndmask_b32_e64 v79, v182, v79, s[40:41]
	v_cmp_lt_i32_e64 s[40:41], v178, v190
	s_or_b64 s[38:39], s[40:41], s[38:39]
	s_or_b64 s[36:37], s[38:39], s[36:37]
	s_or_b64 s[34:35], s[36:37], s[34:35]
	s_or_b64 s[30:31], s[34:35], s[30:31]
	s_or_b64 s[28:29], s[30:31], s[28:29]
	s_or_b64 s[26:27], s[28:29], s[26:27]
	s_or_b64 s[24:25], s[26:27], s[24:25]
	s_or_b64 s[22:23], s[24:25], s[22:23]
	s_or_b64 s[20:21], s[22:23], s[20:21]
	s_or_b64 s[14:15], s[20:21], s[14:15]
	s_or_b64 s[12:13], s[14:15], s[12:13]
	s_or_b64 s[10:11], s[12:13], s[10:11]
	s_or_b64 s[8:9], s[10:11], s[8:9]
	s_or_b64 s[0:1], s[8:9], s[0:1]
	s_or_b64 vcc, s[0:1], vcc
	v_add_u32_e32 v178, 0x60, v142
	v_cndmask_b32_e32 v48, v182, v48, vcc
	v_cmp_lt_i32_e32 vcc, v178, v190
	v_add_u32_e32 v178, 0x61, v142
	v_cndmask_b32_e64 v49, v182, v49, s[0:1]
	v_cmp_lt_i32_e64 s[0:1], v178, v190
	v_add_u32_e32 v178, 0x62, v142
	v_cndmask_b32_e64 v50, v182, v50, s[8:9]
	v_cmp_lt_i32_e64 s[8:9], v178, v190
	v_add_u32_e32 v178, 0x63, v142
	v_cndmask_b32_e64 v51, v182, v51, s[10:11]
	v_cmp_lt_i32_e64 s[10:11], v178, v190
	v_add_u32_e32 v178, 0x68, v142
	v_cndmask_b32_e64 v52, v182, v52, s[12:13]
	v_cmp_lt_i32_e64 s[12:13], v178, v190
	v_add_u32_e32 v178, 0x69, v142
	v_cndmask_b32_e64 v53, v182, v53, s[14:15]
	v_cmp_lt_i32_e64 s[14:15], v178, v190
	v_add_u32_e32 v178, 0x6a, v142
	v_cndmask_b32_e64 v54, v182, v54, s[20:21]
	v_cmp_lt_i32_e64 s[20:21], v178, v190
	v_add_u32_e32 v178, 0x6b, v142
	v_cndmask_b32_e64 v55, v182, v55, s[22:23]
	v_cmp_lt_i32_e64 s[22:23], v178, v190
	v_add_u32_e32 v178, 0x70, v142
	v_cndmask_b32_e64 v56, v182, v56, s[24:25]
	v_cmp_lt_i32_e64 s[24:25], v178, v190
	v_add_u32_e32 v178, 0x71, v142
	v_cndmask_b32_e64 v57, v182, v57, s[26:27]
	v_cmp_lt_i32_e64 s[26:27], v178, v190
	v_add_u32_e32 v178, 0x72, v142
	v_cndmask_b32_e64 v58, v182, v58, s[28:29]
	v_cmp_lt_i32_e64 s[28:29], v178, v190
	v_add_u32_e32 v178, 0x73, v142
	v_cndmask_b32_e64 v59, v182, v59, s[30:31]
	v_cmp_lt_i32_e64 s[30:31], v178, v190
	v_add_u32_e32 v178, 0x78, v142
	v_cndmask_b32_e64 v60, v182, v60, s[34:35]
	v_cmp_lt_i32_e64 s[34:35], v178, v190
	v_add_u32_e32 v178, 0x79, v142
	v_cndmask_b32_e64 v61, v182, v61, s[36:37]
	v_cmp_lt_i32_e64 s[36:37], v178, v190
	v_add_u32_e32 v178, 0x7a, v142
	v_add_u32_e32 v142, 0x7b, v142
	v_cndmask_b32_e64 v63, v182, v63, s[40:41]
	v_cndmask_b32_e64 v62, v182, v62, s[38:39]
	v_cmp_lt_i32_e64 s[38:39], v178, v190
	v_cmp_lt_i32_e64 s[40:41], v142, v190
	s_or_b64 s[38:39], s[40:41], s[38:39]
	s_or_b64 s[36:37], s[38:39], s[36:37]
	s_or_b64 s[34:35], s[36:37], s[34:35]
	s_or_b64 s[30:31], s[34:35], s[30:31]
	s_or_b64 s[28:29], s[30:31], s[28:29]
	s_or_b64 s[26:27], s[28:29], s[26:27]
	s_or_b64 s[24:25], s[26:27], s[24:25]
	s_or_b64 s[22:23], s[24:25], s[22:23]
	s_or_b64 s[20:21], s[22:23], s[20:21]
	s_or_b64 s[14:15], s[20:21], s[14:15]
	s_or_b64 s[12:13], s[14:15], s[12:13]
	s_or_b64 s[10:11], s[12:13], s[10:11]
	s_or_b64 s[8:9], s[10:11], s[8:9]
	s_or_b64 s[0:1], s[8:9], s[0:1]
	s_or_b64 vcc, s[0:1], vcc
	v_cndmask_b32_e64 v47, v182, v47, s[40:41]
	v_cndmask_b32_e64 v46, v182, v46, s[38:39]
	v_cndmask_b32_e64 v45, v182, v45, s[36:37]
	v_cndmask_b32_e64 v44, v182, v44, s[34:35]
	v_cndmask_b32_e64 v43, v182, v43, s[30:31]
	v_cndmask_b32_e64 v42, v182, v42, s[28:29]
	v_cndmask_b32_e64 v41, v182, v41, s[26:27]
	v_cndmask_b32_e64 v40, v182, v40, s[24:25]
	v_cndmask_b32_e64 v39, v182, v39, s[22:23]
	v_cndmask_b32_e64 v38, v182, v38, s[20:21]
	v_cndmask_b32_e64 v37, v182, v37, s[14:15]
	v_cndmask_b32_e64 v36, v182, v36, s[12:13]
	v_cndmask_b32_e64 v35, v182, v35, s[10:11]
	v_cndmask_b32_e64 v34, v182, v34, s[8:9]
	v_cndmask_b32_e64 v33, v182, v33, s[0:1]
	v_cndmask_b32_e32 v32, v182, v32, vcc
	s_branch .LBB0_2287
